# P2 work queue: light items (index >= 512) claim the next item after the item instead of before it (no look-ahead needed), conv items unchanged
# speedup vs baseline: 1.0023x; 1.0023x over previous
.LBB0_503:
	s_cmpk_gt_i32 s37, 0x1ff
	s_cbranch_scc0 .Lq_nolate
	s_barrier
	s_mov_b64 s[76:77], exec
	v_readlane_b32 s4, v253, 1
	v_readlane_b32 s5, v253, 2
	s_and_b64 s[4:5], s[76:77], s[4:5]
	s_mov_b64 exec, s[4:5]
	s_cbranch_execz .Lq_l508
	s_mov_b64 s[90:91], exec
	v_mbcnt_lo_u32_b32 v32, s90, 0
	v_mbcnt_hi_u32_b32 v32, s91, v32
	v_cmp_eq_u32_e32 vcc, 0, v32
	s_and_saveexec_b64 s[88:89], vcc
	s_cbranch_execz .Lq_l507
	s_bcnt1_i32_b64 s0, s[90:91]
	v_mov_b32_e32 v33, s0
	global_atomic_add v33, v53, v33, s[54:55] sc0

.Lq_l508:
	s_or_b64 exec, exec, s[76:77]
	v_mov_b32_e32 v32, s3
	s_waitcnt lgkmcnt(0)
	s_barrier
	ds_read_b32 v32, v32
	s_waitcnt lgkmcnt(0)
	v_readfirstlane_b32 s43, v32

.LBB0_504:
	s_cmpk_gt_i32 s37, 0x1ff
	s_cbranch_scc0 .Lq_pop
	s_xor_b64 s[34:35], s[52:53], -1
	s_mov_b64 s[88:89], -1
	s_branch .Lq_light

.Lq_light:
	s_cmpk_gt_u32 s37, 0x2ff
	s_cbranch_scc0 .LBB0_521
	v_mov_b32_e32 v32, v136
	s_add_i32 s0, s37, 0xfffffd00
	v_readlane_b32 s72, v254, 36
	v_ashrrev_i32_e32 v33, 31, v32
	s_lshl_b32 s5, s0, 2
	v_lshlrev_b64 v[34:35], 2, v[32:33]
	v_readlane_b32 s82, v254, 46
	v_readlane_b32 s83, v254, 47
	s_mulk_i32 s0, 0x3c00
	s_lshl_b64 s[88:89], s[0:1], 2
	v_lshl_add_u64 v[36:37], s[82:83], 0, v[34:35]
	v_lshl_add_u64 v[36:37], v[36:37], 0, s[88:89]
	v_add_co_u32_e32 v38, vcc, 0x1000, v36
	v_readlane_b32 s73, v254, 37
	s_nop 0
	v_addc_co_u32_e32 v39, vcc, 0, v37, vcc
	v_add_co_u32_e32 v44, vcc, 0x2000, v36
	v_readlane_b32 s74, v254, 38
	s_nop 0
	v_addc_co_u32_e32 v45, vcc, 0, v37, vcc
	v_add_co_u32_e32 v46, vcc, 0x3000, v36
	v_readlane_b32 s75, v254, 39
	s_nop 0
	v_addc_co_u32_e32 v47, vcc, 0, v37, vcc
	global_load_dword v88, v[36:37], off
	global_load_dword v89, v[36:37], off offset:2048
	global_load_dword v87, v[38:39], off
	global_load_dword v43, v[38:39], off offset:2048
	global_load_dword v41, v[44:45], off
	s_nop 0
	global_load_dword v39, v[44:45], off offset:2048
	global_load_dword v42, v[46:47], off
	global_load_dword v40, v[46:47], off offset:2048
	v_add_co_u32_e32 v46, vcc, 0x4000, v36
	v_readlane_b32 s76, v254, 40
	s_nop 0
	v_addc_co_u32_e32 v47, vcc, 0, v37, vcc
	global_load_dword v45, v[46:47], off
	global_load_dword v44, v[46:47], off offset:2048
	v_add_co_u32_e32 v46, vcc, 0x5000, v36
	v_readlane_b32 s77, v254, 41
	s_nop 0
	v_addc_co_u32_e32 v47, vcc, 0, v37, vcc
	v_add_co_u32_e32 v74, vcc, 0x6000, v36
	v_readlane_b32 s78, v254, 42
	s_nop 0
	v_addc_co_u32_e32 v75, vcc, 0, v37, vcc
	v_add_co_u32_e32 v78, vcc, 0x7000, v36
	v_readlane_b32 s79, v254, 43
	s_nop 0
	v_addc_co_u32_e32 v79, vcc, 0, v37, vcc
	global_load_dword v51, v[46:47], off
	global_load_dword v50, v[46:47], off offset:2048
	global_load_dword v48, v[74:75], off
	s_nop 0
	global_load_dword v46, v[74:75], off offset:2048
	global_load_dword v49, v[78:79], off
	global_load_dword v47, v[78:79], off offset:2048
	v_add_co_u32_e32 v74, vcc, 0x8000, v36
	v_readlane_b32 s80, v254, 44
	s_nop 0
	v_addc_co_u32_e32 v75, vcc, 0, v37, vcc
	global_load_dword v72, v[74:75], off
	global_load_dword v52, v[74:75], off offset:2048
	v_add_co_u32_e32 v74, vcc, 0x9000, v36
	v_readlane_b32 s81, v254, 45
	s_nop 0
	v_addc_co_u32_e32 v75, vcc, 0, v37, vcc
	v_add_co_u32_e32 v82, vcc, 0xa000, v36
	v_readlane_b32 s84, v254, 48
	s_nop 0
	v_addc_co_u32_e32 v83, vcc, 0, v37, vcc
	v_add_co_u32_e32 v84, vcc, 0xb000, v36
	v_readlane_b32 s85, v254, 49
	s_nop 0
	v_addc_co_u32_e32 v85, vcc, 0, v37, vcc
	global_load_dword v80, v[74:75], off
	global_load_dword v79, v[74:75], off offset:2048
	global_load_dword v76, v[82:83], off
	s_nop 0
	global_load_dword v74, v[82:83], off offset:2048
	global_load_dword v78, v[84:85], off
	global_load_dword v75, v[84:85], off offset:2048
	v_add_co_u32_e32 v84, vcc, 0xc000, v36
	v_readlane_b32 s86, v254, 50
	s_nop 0
	v_addc_co_u32_e32 v85, vcc, 0, v37, vcc
	global_load_dword v82, v[84:85], off
	global_load_dword v81, v[84:85], off offset:2048
	v_add_co_u32_e32 v90, vcc, 0xd000, v36
	v_readlane_b32 s87, v254, 51
	s_nop 0
	v_addc_co_u32_e32 v91, vcc, 0, v37, vcc
	v_add_co_u32_e32 v36, vcc, 0xe000, v36
	v_readlane_b32 s72, v254, 4
	s_nop 0
	v_addc_co_u32_e32 v37, vcc, 0, v37, vcc
	global_load_dword v85, v[90:91], off
	global_load_dword v83, v[90:91], off offset:2048
	global_load_dword v86, v[36:37], off
	global_load_dword v84, v[36:37], off offset:2048
	s_or_b32 s33, s5, 0x4000
	v_readlane_b32 s73, v254, 5
	v_readlane_b32 s74, v254, 6
	v_readlane_b32 s75, v254, 7
	v_readlane_b32 s76, v254, 8
	v_readlane_b32 s77, v254, 9
	v_readlane_b32 s78, v254, 10
	v_readlane_b32 s79, v254, 11
	v_readlane_b32 s80, v254, 12
	v_readlane_b32 s81, v254, 13
	v_readlane_b32 s82, v254, 14
	v_readlane_b32 s83, v254, 15
	v_readlane_b32 s84, v254, 16
	v_readlane_b32 s85, v254, 17
	v_readlane_b32 s86, v254, 18
	v_readlane_b32 s87, v254, 19
	v_lshl_add_u64 v[36:37], v[32:33], 1, s[82:83]
	s_lshl_b32 s0, s33, 10
	v_readlane_b32 s72, v254, 52
	v_lshl_add_u64 v[90:91], v[36:37], 0, s[0:1]
	v_readlane_b32 s84, v255, 0
	v_readlane_b32 s85, v255, 1
	global_load_ushort v185, v[90:91], off
	s_movk_i32 s0, 0x1000
	v_lshl_add_u64 v[90:91], s[84:85], 0, v[34:35]
	v_lshl_add_u64 v[90:91], v[90:91], 0, s[88:89]
	v_add_co_u32_e32 v92, vcc, s0, v90
	s_movk_i32 s4, 0x2000
	s_nop 0
	v_addc_co_u32_e32 v93, vcc, 0, v91, vcc
	v_add_co_u32_e32 v94, vcc, s4, v90
	s_movk_i32 s6, 0x3000
	s_nop 0
	v_addc_co_u32_e32 v95, vcc, 0, v91, vcc
	s_waitcnt vmcnt(26)
	global_store_dword v[90:91], v41, off
	s_waitcnt vmcnt(26)
	global_store_dword v[90:91], v39, off offset:2048
	s_waitcnt vmcnt(26)
	global_store_dword v[94:95], v42, off offset:-4096
	s_waitcnt vmcnt(26)
	global_store_dword v[92:93], v40, off offset:2048
	s_waitcnt vmcnt(26)
	global_store_dword v[94:95], v45, off
	s_waitcnt vmcnt(26)
	global_store_dword v[94:95], v44, off offset:2048
	v_add_co_u32_e32 v92, vcc, s6, v90
	s_movk_i32 s7, 0x4000
	s_nop 0
	v_addc_co_u32_e32 v93, vcc, 0, v91, vcc
	v_add_co_u32_e32 v94, vcc, s7, v90
	s_movk_i32 s8, 0x5000
	s_nop 0
	v_addc_co_u32_e32 v95, vcc, 0, v91, vcc
	s_waitcnt vmcnt(26)
	global_store_dword v[94:95], v51, off offset:-4096
	s_waitcnt vmcnt(26)
	global_store_dword v[92:93], v50, off offset:2048
	s_waitcnt vmcnt(26)
	global_store_dword v[94:95], v48, off
	s_waitcnt vmcnt(26)
	global_store_dword v[94:95], v46, off offset:2048
	v_add_co_u32_e32 v92, vcc, s8, v90
	s_movk_i32 s9, 0x6000
	s_nop 0
	v_addc_co_u32_e32 v93, vcc, 0, v91, vcc
	v_add_co_u32_e32 v94, vcc, s9, v90
	s_movk_i32 s10, 0x7000
	s_nop 0
	v_addc_co_u32_e32 v95, vcc, 0, v91, vcc
	s_waitcnt vmcnt(26)
	global_store_dword v[94:95], v49, off offset:-4096
	s_waitcnt vmcnt(26)
	global_store_dword v[92:93], v47, off offset:2048
	s_waitcnt vmcnt(26)
	global_store_dword v[94:95], v72, off
	s_waitcnt vmcnt(26)
	global_store_dword v[94:95], v52, off offset:2048
	v_add_co_u32_e32 v92, vcc, s10, v90
	s_mov_b32 s11, 0x8000
	s_nop 0
	v_addc_co_u32_e32 v93, vcc, 0, v91, vcc
	v_add_co_u32_e32 v94, vcc, s11, v90
	s_mov_b32 s12, 0x9000
	s_nop 0
	v_addc_co_u32_e32 v95, vcc, 0, v91, vcc
	s_waitcnt vmcnt(26)
	global_store_dword v[94:95], v80, off offset:-4096
	s_waitcnt vmcnt(26)
	global_store_dword v[92:93], v79, off offset:2048
	s_waitcnt vmcnt(26)
	global_store_dword v[94:95], v76, off
	s_waitcnt vmcnt(26)
	global_store_dword v[94:95], v74, off offset:2048
	v_add_co_u32_e32 v92, vcc, s12, v90
	s_mov_b32 s13, 0xa000
	s_nop 0
	v_addc_co_u32_e32 v93, vcc, 0, v91, vcc
	v_add_co_u32_e32 v94, vcc, s13, v90
	s_mov_b32 s14, 0xb000
	s_nop 0
	v_addc_co_u32_e32 v95, vcc, 0, v91, vcc
	v_readlane_b32 s73, v254, 53
	v_readlane_b32 s74, v254, 54
	v_readlane_b32 s75, v254, 55
	v_readlane_b32 s76, v254, 56
	v_readlane_b32 s77, v254, 57
	v_readlane_b32 s78, v254, 58
	v_readlane_b32 s79, v254, 59
	v_readlane_b32 s80, v254, 60
	v_readlane_b32 s81, v254, 61
	v_readlane_b32 s82, v254, 62
	v_readlane_b32 s83, v254, 63
	v_readlane_b32 s86, v255, 2
	v_readlane_b32 s87, v255, 3
	s_waitcnt vmcnt(26)
	global_store_dword v[94:95], v78, off offset:-4096
	s_waitcnt vmcnt(26)
	global_store_dword v[92:93], v75, off offset:2048
	s_waitcnt vmcnt(26)
	global_store_dword v[94:95], v82, off
	s_waitcnt vmcnt(26)
	global_store_dword v[94:95], v81, off offset:2048
	v_add_co_u32_e32 v92, vcc, s14, v90
	s_mov_b32 s15, 0xc000
	s_nop 0
	v_addc_co_u32_e32 v93, vcc, 0, v91, vcc
	v_readlane_b32 s72, v253, 3
	v_add_co_u32_e32 v90, vcc, s15, v90
	v_readlane_b32 s78, v253, 9
	v_readlane_b32 s79, v253, 10
	v_addc_co_u32_e32 v91, vcc, 0, v91, vcc
	s_nop 0
	v_lshl_add_u64 v[176:177], s[78:79], 0, v[34:35]
	v_add_co_u32_e32 v94, vcc, s0, v176
	v_readlane_b32 s80, v253, 11
	s_nop 0
	v_addc_co_u32_e32 v95, vcc, 0, v177, vcc
	v_add_co_u32_e32 v154, vcc, s4, v176
	v_readlane_b32 s81, v253, 12
	s_nop 0
	v_addc_co_u32_e32 v155, vcc, 0, v177, vcc
	v_add_co_u32_e32 v162, vcc, s6, v176
	s_waitcnt vmcnt(26)
	global_store_dword v[90:91], v85, off offset:-4096
	s_waitcnt vmcnt(26)
	global_store_dword v[92:93], v83, off offset:2048
	s_waitcnt vmcnt(26)
	global_store_dword v[90:91], v86, off
	s_waitcnt vmcnt(26)
	global_store_dword v[90:91], v84, off offset:2048
	v_addc_co_u32_e32 v163, vcc, 0, v177, vcc
	v_add_co_u32_e32 v156, vcc, s7, v176
	v_lshl_add_u64 v[90:91], s[80:81], 0, v[34:35]
	s_nop 0
	v_addc_co_u32_e32 v157, vcc, 0, v177, vcc
	v_add_co_u32_e32 v164, vcc, s8, v176
	global_load_dword v38, v[90:91], off
	s_nop 0
	v_addc_co_u32_e32 v165, vcc, 0, v177, vcc
	global_load_dword v92, v[176:177], off
	global_load_dword v91, v[176:177], off offset:2048
	global_load_dword v90, v[94:95], off offset:2048
	global_load_dword v153, v[154:155], off offset:-4096
	global_load_dword v96, v[154:155], off
	s_nop 0
	global_load_dword v95, v[154:155], off offset:2048
	global_load_dword v97, v[156:157], off offset:-4096
	global_load_dword v94, v[156:157], off
	global_load_dword v93, v[156:157], off offset:2048
	v_add_co_u32_e32 v154, vcc, s9, v176
	s_mov_b32 s0, 0xd000
	s_nop 0
	v_addc_co_u32_e32 v155, vcc, 0, v177, vcc
	v_add_co_u32_e32 v166, vcc, s10, v176
	s_or_b32 s4, s5, 0x4001
	s_nop 0
	v_addc_co_u32_e32 v167, vcc, 0, v177, vcc
	v_add_co_u32_e32 v168, vcc, s11, v176
	s_or_b32 s91, s5, 0x4002
	s_nop 0
	v_addc_co_u32_e32 v169, vcc, 0, v177, vcc
	v_add_co_u32_e32 v170, vcc, s12, v176
	s_or_b32 s90, s5, 0x4003
	s_nop 0
	v_addc_co_u32_e32 v171, vcc, 0, v177, vcc
	v_add_co_u32_e32 v178, vcc, s13, v176
	v_xor_b32_e32 v188, 2, v152
	s_nop 0
	v_addc_co_u32_e32 v179, vcc, 0, v177, vcc
	global_load_dword v161, v[154:155], off offset:-4096
	global_load_dword v160, v[154:155], off
	global_load_dword v159, v[154:155], off offset:2048
	global_load_dword v158, v[168:169], off offset:-4096
	global_load_dword v156, v[168:169], off
	s_nop 0
	global_load_dword v155, v[168:169], off offset:2048
	global_load_dword v157, v[178:179], off offset:-4096
	global_load_dword v154, v[178:179], off
	v_add_co_u32_e32 v168, vcc, s14, v176
	v_readlane_b32 s73, v253, 4
	s_nop 0
	v_addc_co_u32_e32 v169, vcc, 0, v177, vcc
	global_load_dword v175, v[162:163], off offset:2048
	global_load_dword v172, v[164:165], off offset:2048
	s_nop 0
	global_load_dword v167, v[166:167], off offset:2048
	s_nop 0
	global_load_dword v163, v[170:171], off offset:2048
	global_load_dword v162, v[168:169], off offset:2048
	v_add_co_u32_e32 v180, vcc, s15, v176
	v_readlane_b32 s74, v253, 5
	s_nop 0
	v_addc_co_u32_e32 v181, vcc, 0, v177, vcc
	v_add_co_u32_e32 v164, vcc, s0, v176
	s_mov_b32 s0, 0xe000
	s_nop 0
	v_addc_co_u32_e32 v165, vcc, 0, v177, vcc
	v_add_co_u32_e32 v182, vcc, s0, v176
	s_mov_b32 s0, 0xf000
	s_nop 0
	v_addc_co_u32_e32 v183, vcc, 0, v177, vcc
	global_load_dword v164, v[164:165], off offset:2048
	s_nop 0
	global_load_dword v174, v[178:179], off offset:2048
	global_load_dword v173, v[180:181], off offset:-4096
	global_load_dword v171, v[180:181], off
	global_load_dword v170, v[180:181], off offset:2048
	global_load_dword v168, v[182:183], off offset:-4096
	global_load_dword v166, v[182:183], off
	global_load_dword v165, v[182:183], off offset:2048
	v_add_co_u32_e32 v176, vcc, s0, v176
	s_lshl_b32 s0, s4, 10
	s_nop 0
	v_addc_co_u32_e32 v177, vcc, 0, v177, vcc
	global_load_dword v169, v[176:177], off
	v_lshl_add_u64 v[176:177], v[36:37], 0, s[0:1]
	s_lshl_b32 s0, s91, 10
	v_lshl_add_u64 v[178:179], v[36:37], 0, s[0:1]
	s_lshl_b32 s0, s90, 10
	v_lshl_add_u64 v[36:37], v[36:37], 0, s[0:1]
	global_load_ushort v183, v[176:177], off
	global_load_ushort v184, v[178:179], off
	s_nop 0
	global_load_ushort v179, v[36:37], off
	v_and_b32_e32 v176, 64, v152
	v_add_u32_e32 v182, 64, v176
	v_xor_b32_e32 v176, 32, v152
	s_waitcnt vmcnt(61)
	v_lshlrev_b32_e32 v36, 16, v185
	v_cmp_lt_i32_e32 vcc, v176, v182
	v_xor_b32_e32 v177, 8, v152
	v_xor_b32_e32 v180, 4, v152
	v_cndmask_b32_e32 v176, v152, v176, vcc
	v_lshlrev_b32_e32 v178, 2, v176
	v_xor_b32_e32 v176, 16, v152
	v_cmp_lt_i32_e32 vcc, v176, v182
	v_and_b32_e32 v37, 63, v32
	v_readlane_b32 s75, v253, 6
	v_cndmask_b32_e32 v176, v152, v176, vcc
	v_lshlrev_b32_e32 v176, 2, v176
	v_cmp_lt_i32_e32 vcc, v177, v182
	s_waitcnt vmcnt(33)
	v_fma_f32 v88, v88, v92, v38
	s_waitcnt vmcnt(32)
	v_fmac_f32_e32 v88, v89, v91
	s_waitcnt vmcnt(30)
	v_fmac_f32_e32 v88, v87, v153
	v_fmac_f32_e32 v88, v43, v90
	s_waitcnt vmcnt(29)
	v_fmac_f32_e32 v88, v41, v96
	s_waitcnt vmcnt(28)
	v_fmac_f32_e32 v88, v39, v95
	s_waitcnt vmcnt(27)
	v_fmac_f32_e32 v88, v42, v97
	v_cndmask_b32_e32 v177, v152, v177, vcc
	v_lshlrev_b32_e32 v177, 2, v177
	v_cmp_lt_i32_e32 vcc, v180, v182
	v_readlane_b32 s76, v253, 7
	v_readlane_b32 s77, v253, 8
	v_cndmask_b32_e32 v180, v152, v180, vcc
	v_lshlrev_b32_e32 v180, 2, v180
	v_cmp_lt_i32_e32 vcc, v188, v182
	v_readlane_b32 s82, v253, 13
	v_readlane_b32 s83, v253, 14
	v_cndmask_b32_e32 v188, v152, v188, vcc
	v_readlane_b32 s84, v253, 15
	v_readlane_b32 s85, v253, 16
	v_readlane_b32 s86, v253, 17
	v_readlane_b32 s87, v253, 18
	s_barrier
	s_waitcnt vmcnt(16)
	v_fmac_f32_e32 v88, v40, v175
	v_fmac_f32_e32 v88, v45, v94
	v_fmac_f32_e32 v88, v44, v93
	v_fmac_f32_e32 v88, v51, v161
	s_waitcnt vmcnt(15)
	v_fmac_f32_e32 v88, v50, v172
	v_fmac_f32_e32 v88, v48, v160
	v_fmac_f32_e32 v88, v46, v159
	v_fmac_f32_e32 v88, v49, v158
	s_waitcnt vmcnt(14)
	v_fmac_f32_e32 v88, v47, v167
	v_fmac_f32_e32 v88, v72, v156
	v_fmac_f32_e32 v88, v52, v155
	v_fmac_f32_e32 v88, v80, v157
	s_waitcnt vmcnt(13)
	v_fmac_f32_e32 v88, v79, v163
	v_fmac_f32_e32 v88, v76, v154
	s_waitcnt vmcnt(10)
	v_fmac_f32_e32 v88, v74, v174
	s_waitcnt vmcnt(9)
	v_fmac_f32_e32 v88, v78, v173
	v_fmac_f32_e32 v88, v75, v162
	s_waitcnt vmcnt(8)
	v_fmac_f32_e32 v88, v82, v171
	s_waitcnt vmcnt(7)
	v_fmac_f32_e32 v88, v81, v170
	s_waitcnt vmcnt(6)
	v_fmac_f32_e32 v88, v85, v168
	v_fmac_f32_e32 v88, v83, v164
	s_waitcnt vmcnt(5)
	v_fmac_f32_e32 v88, v86, v166
	s_waitcnt vmcnt(4)
	v_fmac_f32_e32 v88, v84, v165
	s_waitcnt vmcnt(3)
	v_fmac_f32_e32 v88, v169, v36
	v_mul_f32_e32 v185, v88, v88
	ds_bpermute_b32 v181, v178, v88
	ds_bpermute_b32 v185, v178, v185
	s_waitcnt lgkmcnt(1)
	v_add_f32_e32 v181, v88, v181
	s_waitcnt lgkmcnt(0)
	v_fmac_f32_e32 v185, v88, v88
	ds_bpermute_b32 v186, v176, v181
	ds_bpermute_b32 v187, v176, v185
	s_waitcnt lgkmcnt(1)
	v_add_f32_e32 v181, v181, v186
	s_waitcnt lgkmcnt(0)
	v_add_f32_e32 v185, v185, v187
	ds_bpermute_b32 v186, v177, v181
	ds_bpermute_b32 v187, v177, v185
	s_waitcnt lgkmcnt(1)
	v_add_f32_e32 v186, v181, v186
	s_waitcnt lgkmcnt(0)
	v_add_f32_e32 v185, v185, v187
	ds_bpermute_b32 v189, v180, v186
	ds_bpermute_b32 v187, v180, v185
	v_lshlrev_b32_e32 v181, 2, v188
	v_xor_b32_e32 v188, 1, v152
	v_cmp_lt_i32_e32 vcc, v188, v182
	s_waitcnt lgkmcnt(1)
	v_add_f32_e32 v186, v186, v189
	s_waitcnt lgkmcnt(0)
	v_add_f32_e32 v187, v185, v187
	ds_bpermute_b32 v189, v181, v186
	ds_bpermute_b32 v190, v181, v187
	v_cndmask_b32_e32 v182, v152, v188, vcc
	v_lshlrev_b32_e32 v182, 2, v182
	v_cmp_eq_u32_e32 vcc, 0, v37
	s_waitcnt lgkmcnt(1)
	v_add_f32_e32 v185, v186, v189
	s_waitcnt lgkmcnt(0)
	v_add_f32_e32 v187, v187, v190
	ds_bpermute_b32 v186, v182, v185
	ds_bpermute_b32 v188, v182, v187
	v_lshl_add_u32 v37, v32, 2, 0
	s_and_saveexec_b64 s[88:89], vcc
	s_cbranch_execz .LBB0_512
	s_waitcnt lgkmcnt(1)
	v_add_f32_e32 v185, v185, v186
	s_waitcnt lgkmcnt(0)
	v_add_f32_e32 v186, v187, v188
	ds_write2_b32 v37, v185, v186 offset1:32
